# norm2 phase: next row pair loaded before the current pair is reduced and stored, scalar loop control
# speedup vs baseline: 1.0052x; 1.0029x over previous
; __device__ __forceinline__ void norm_phase(const float* H, const float* g, bf16_t* HN) {
;     ...
;   for (int row = gw; row < NREAL + 64; row += 2 * nw) {
;     const int row2 = row + nw < NREAL + 64 ? row + nw : row;
;     const float* p = H + (size_t)row * DM + lane * 8; const float* p2 = H + (size_t)row2 * DM + lane * 8; f32x4 v[4], u[4]; float ss = 0.f, ss2 = 0.f;
; #pragma unroll
;     for (int i = 0; i < 4; ++i) { v[i] = *(const f32x4*)(p + 512 * (i >> 1) + 4 * (i & 1)); u[i] = *(const f32x4*)(p2 + 512 * (i >> 1) + 4 * (i & 1)); }
; #pragma unroll
;     for (int i = 0; i < 4; ++i) { ss += v[i][0] * v[i][0] + v[i][1] * v[i][1] + v[i][2] * v[i][2] + v[i][3] * v[i][3]; ss2 += u[i][0] * u[i][0] + u[i][1] * u[i][1] + u[i][2] * u[i][2] + u[i][3] * u[i][3]; }
;     ss = wave_sum(ss); ss2 = wave_sum(ss2); const float rs = rsqrtf(ss * (1.0f / 1024.0f) + 1e-6f), rs2 = rsqrtf(ss2 * (1.0f / 1024.0f) + 1e-6f);
.LBB0_1501:
	v_readfirstlane_b32 s0, v54
	s_nop 3
	s_add_i32 s9, s0, s24
	s_cmp_lt_i32 s9, s49
	s_cselect_b32 s9, s9, s0
	s_lshl_b32 s10, s0, 12
	s_lshl_b32 s4, s9, 12
	v_mov_b32_e32 v62, s10
	v_mov_b32_e32 v63, 0
	v_lshl_add_u64 v[58:59], v[50:51], 0, v[62:63]
	v_mov_b32_e32 v62, s4
	v_lshl_add_u64 v[60:61], v[50:51], 0, v[62:63]
	global_load_dwordx4 v[46:49], v[58:59], off
	global_load_dwordx4 v[42:45], v[58:59], off offset:16
	global_load_dwordx4 v[38:41], v[60:61], off
	global_load_dwordx4 v[34:37], v[60:61], off offset:16
	global_load_dwordx4 v[30:33], v[58:59], off offset:2048
	global_load_dwordx4 v[26:29], v[58:59], off offset:2064
	global_load_dwordx4 v[22:25], v[60:61], off offset:2048
	global_load_dwordx4 v[18:21], v[60:61], off offset:2064
	s_lshl_b32 s10, s0, 11
	s_lshl_b32 s4, s9, 11
	v_mov_b32_e32 v62, s10
	v_lshl_add_u64 v[54:55], v[52:53], 0, v[62:63]
	v_mov_b32_e32 v62, s4
	v_lshl_add_u64 v[56:57], v[52:53], 0, v[62:63]
	s_lshl_b32 s8, s24, 1
	s_add_i32 s1, s0, s8
	s_cmp_lt_i32 s1, s49
	s_cbranch_scc0 .Ln2_lastA_first
	s_add_i32 s9, s1, s24
	s_cmp_lt_i32 s9, s49
	s_cselect_b32 s9, s9, s1
	s_lshl_b32 s10, s1, 12
	s_lshl_b32 s4, s9, 12
	v_mov_b32_e32 v62, s10
	v_mov_b32_e32 v63, 0
	v_lshl_add_u64 v[58:59], v[50:51], 0, v[62:63]
	v_mov_b32_e32 v62, s4
	v_lshl_add_u64 v[60:61], v[50:51], 0, v[62:63]
	global_load_dwordx4 v[100:103], v[58:59], off
	global_load_dwordx4 v[96:99], v[58:59], off offset:16
	global_load_dwordx4 v[92:95], v[60:61], off
	global_load_dwordx4 v[88:91], v[60:61], off offset:16
	global_load_dwordx4 v[82:85], v[58:59], off offset:2048
	global_load_dwordx4 v[78:81], v[58:59], off offset:2064
	global_load_dwordx4 v[74:77], v[60:61], off offset:2048
	global_load_dwordx4 v[70:73], v[60:61], off offset:2064
	s_lshl_b32 s10, s1, 11
	s_lshl_b32 s4, s9, 11
	v_mov_b32_e32 v62, s10
	v_lshl_add_u64 v[128:129], v[52:53], 0, v[62:63]
	v_mov_b32_e32 v62, s4
	v_lshl_add_u64 v[130:131], v[52:53], 0, v[62:63]
	s_waitcnt vmcnt(8)
	v_mov_b32_e32 v60, v47
	v_mov_b32_e32 v61, v43
	v_mov_b32_e32 v58, v46
	v_mov_b32_e32 v59, v42
	v_pk_mul_f32 v[60:61], v[60:61], v[60:61]
	v_mov_b32_e32 v62, v39
	v_pk_fma_f32 v[58:59], v[58:59], v[58:59], v[60:61]
	v_mov_b32_e32 v60, v48
	v_mov_b32_e32 v61, v44
	v_pk_fma_f32 v[58:59], v[60:61], v[60:61], v[58:59]
	v_mov_b32_e32 v60, v49
	v_mov_b32_e32 v61, v45
	v_mov_b32_e32 v63, v35
	v_pk_fma_f32 v[58:59], v[60:61], v[60:61], v[58:59]
	v_mov_b32_e32 v60, v38
	v_mov_b32_e32 v61, v34
	v_pk_mul_f32 v[62:63], v[62:63], v[62:63]
	v_mov_b32_e32 v64, v31
	v_pk_fma_f32 v[60:61], v[60:61], v[60:61], v[62:63]
	v_mov_b32_e32 v62, v40
	v_mov_b32_e32 v63, v36
	v_pk_fma_f32 v[60:61], v[62:63], v[62:63], v[60:61]
	v_mov_b32_e32 v62, v41
	v_mov_b32_e32 v63, v37
	v_mov_b32_e32 v65, v27
	v_pk_fma_f32 v[60:61], v[62:63], v[62:63], v[60:61]
	v_mov_b32_e32 v62, v30
	v_mov_b32_e32 v63, v26
	v_pk_mul_f32 v[64:65], v[64:65], v[64:65]
	v_mov_b32_e32 v66, v23
	v_pk_fma_f32 v[62:63], v[62:63], v[62:63], v[64:65]
	v_mov_b32_e32 v64, v32
	v_mov_b32_e32 v65, v28
	v_pk_fma_f32 v[62:63], v[64:65], v[64:65], v[62:63]
	v_mov_b32_e32 v64, v33
	v_mov_b32_e32 v65, v29
	v_mov_b32_e32 v67, v19
	v_pk_fma_f32 v[62:63], v[64:65], v[64:65], v[62:63]
	v_mov_b32_e32 v64, v22
	v_mov_b32_e32 v65, v18
	v_pk_mul_f32 v[66:67], v[66:67], v[66:67]
	s_nop 0
	v_pk_fma_f32 v[64:65], v[64:65], v[64:65], v[66:67]
	v_mov_b32_e32 v66, v24
	v_mov_b32_e32 v67, v20
	v_pk_fma_f32 v[64:65], v[66:67], v[66:67], v[64:65]
	v_mov_b32_e32 v66, v25
	v_mov_b32_e32 v67, v21
	v_pk_fma_f32 v[64:65], v[66:67], v[66:67], v[64:65]
	v_mov_b32_e32 v66, v210
	v_mov_b32_e32 v67, v58
	v_lshlrev_b32_e32 v66, 2, v66
	v_xor_b32_e32 v68, 0x80, v66
	v_mov_b32_e32 v66, v210
	v_mov_b32_e32 v58, v61
	v_lshlrev_b32_e32 v66, 2, v66
	v_xor_b32_e32 v69, 0x80, v66
	v_mov_b32_e32 v66, v60
	v_pk_add_f32 v[58:59], v[66:67], v[58:59]
	v_mov_b32_e32 v60, v64
	v_mov_b32_e32 v61, v62
	v_pk_add_f32 v[58:59], v[58:59], v[60:61]
	v_mov_b32_e32 v62, v65
	v_pk_add_f32 v[58:59], v[58:59], v[62:63]
	ds_swizzle_b32 v61, v59 offset:swizzle(SWAP,16)
	ds_swizzle_b32 v60, v58 offset:swizzle(SWAP,16)
	s_waitcnt lgkmcnt(0)
	v_pk_add_f32 v[58:59], v[58:59], v[60:61]
	ds_swizzle_b32 v61, v59 offset:swizzle(SWAP,8)
	ds_swizzle_b32 v60, v58 offset:swizzle(SWAP,8)
	s_waitcnt lgkmcnt(0)
	v_pk_add_f32 v[58:59], v[58:59], v[60:61]
	ds_swizzle_b32 v61, v59 offset:swizzle(SWAP,4)
	ds_swizzle_b32 v60, v58 offset:swizzle(SWAP,4)
	s_waitcnt lgkmcnt(0)
	v_pk_add_f32 v[58:59], v[58:59], v[60:61]
	ds_swizzle_b32 v61, v59 offset:swizzle(SWAP,2)
	ds_swizzle_b32 v60, v58 offset:swizzle(SWAP,2)
	s_waitcnt lgkmcnt(0)
	v_pk_add_f32 v[58:59], v[58:59], v[60:61]
	ds_swizzle_b32 v61, v59 offset:swizzle(SWAP,1)
	ds_swizzle_b32 v60, v58 offset:swizzle(SWAP,1)
	s_waitcnt lgkmcnt(0)
	v_pk_add_f32 v[58:59], v[58:59], v[60:61]
	ds_bpermute_b32 v61, v68, v59
	ds_bpermute_b32 v60, v69, v58
	s_waitcnt lgkmcnt(0)
; __device__ __forceinline__ void store8bf(bf16_t* p, f32x4 v0, f32x4 v1) { u32x4 w; w.x = cvt_pk_bf16(v0[0], v0[1]); w.y = cvt_pk_bf16(v0[2], v0[3]); w.z = cvt_pk_bf16(v1[0], v1[1]); w.w = cvt_pk_bf16(v1[2], v1[3]); *(u32x4*)p = w; }
; __device__ __forceinline__ void norm_phase(const float* H, const float* g, bf16_t* HN) {
;     ...
;   for (int row = gw; row < NREAL + 64; row += 2 * nw) {
;     const int row2 = row + nw < NREAL + 64 ? row + nw : row;
;     const float* p = H + (size_t)row * DM + lane * 8; const float* p2 = H + (size_t)row2 * DM + lane * 8; f32x4 v[4], u[4]; float ss = 0.f, ss2 = 0.f;
; #pragma unroll
;     for (int i = 0; i < 4; ++i) { v[i] = *(const f32x4*)(p + 512 * (i >> 1) + 4 * (i & 1)); u[i] = *(const f32x4*)(p2 + 512 * (i >> 1) + 4 * (i & 1)); }
;     ...
;     ss = wave_sum(ss); ss2 = wave_sum(ss2); const float rs = rsqrtf(ss * (1.0f / 1024.0f) + 1e-6f), rs2 = rsqrtf(ss2 * (1.0f / 1024.0f) + 1e-6f);
;     bf16_t* q = HN + (size_t)row * DM + lane * 8; bf16_t* q2 = HN + (size_t)row2 * DM + lane * 8;
; #pragma unroll
;     for (int i = 0; i < 2; ++i) { store8bf(q + 512 * i, v[2 * i] * rs * gv[2 * i], v[2 * i + 1] * rs * gv[2 * i + 1]); store8bf(q2 + 512 * i, u[2 * i] * rs2 * gv[2 * i], u[2 * i + 1] * rs2 * gv[2 * i + 1]); }
;   }
	v_pk_add_f32 v[58:59], v[58:59], v[60:61]
	s_nop 0
	v_pk_fma_f32 v[58:59], v[58:59], s[58:59], v[154:155] op_sel_hi:[1,0,0]
	s_nop 0
	v_mul_f32_e32 v60, 0x4b800000, v59
	v_cmp_gt_f32_e64 s[4:5], s46, v59
	v_cmp_gt_f32_e32 vcc, s46, v58
	s_nop 0
	v_cndmask_b32_e64 v59, v59, v60, s[4:5]
	v_rsq_f32_e32 v59, v59
	s_nop 0
	v_mul_f32_e32 v60, 0x45800000, v59
	v_cndmask_b32_e64 v60, v59, v60, s[4:5]
	v_mul_f32_e32 v59, 0x4b800000, v58
	v_cndmask_b32_e32 v58, v58, v59, vcc
	v_rsq_f32_e32 v58, v58
	v_pk_mul_f32 v[46:47], v[46:47], v[60:61] op_sel_hi:[1,0]
	v_pk_mul_f32 v[48:49], v[48:49], v[60:61] op_sel_hi:[1,0]
	v_pk_mul_f32 v[42:43], v[42:43], v[60:61] op_sel_hi:[1,0]
	v_mul_f32_e32 v59, 0x45800000, v58
	v_pk_mul_f32 v[44:45], v[44:45], v[60:61] op_sel_hi:[1,0]
	v_cndmask_b32_e32 v58, v58, v59, vcc
	v_pk_mul_f32 v[48:49], v[8:9], v[48:49]
	v_pk_mul_f32 v[46:47], v[6:7], v[46:47]
	v_pk_mul_f32 v[62:63], v[4:5], v[44:45]
	v_pk_mul_f32 v[44:45], v[2:3], v[42:43]
	v_cvt_pk_bf16_f32 v42, v46, v47
	v_cvt_pk_bf16_f32 v43, v48, v49
	v_cvt_pk_bf16_f32 v44, v44, v45
	v_cvt_pk_bf16_f32 v45, v62, v63
	v_pk_mul_f32 v[38:39], v[38:39], v[58:59] op_sel_hi:[1,0]
	v_pk_mul_f32 v[40:41], v[40:41], v[58:59] op_sel_hi:[1,0]
	v_pk_mul_f32 v[34:35], v[34:35], v[58:59] op_sel_hi:[1,0]
	v_pk_mul_f32 v[36:37], v[36:37], v[58:59] op_sel_hi:[1,0]
	global_store_dwordx4 v[54:55], v[42:45], off
	v_pk_mul_f32 v[40:41], v[8:9], v[40:41]
	v_pk_mul_f32 v[38:39], v[6:7], v[38:39]
	v_pk_mul_f32 v[42:43], v[4:5], v[36:37]
	v_pk_mul_f32 v[36:37], v[2:3], v[34:35]
	v_cvt_pk_bf16_f32 v34, v38, v39
	v_cvt_pk_bf16_f32 v35, v40, v41
	v_cvt_pk_bf16_f32 v36, v36, v37
	v_cvt_pk_bf16_f32 v37, v42, v43
	v_pk_mul_f32 v[30:31], v[30:31], v[60:61] op_sel_hi:[1,0]
	v_pk_mul_f32 v[32:33], v[32:33], v[60:61] op_sel_hi:[1,0]
	v_pk_mul_f32 v[26:27], v[26:27], v[60:61] op_sel_hi:[1,0]
	v_pk_mul_f32 v[28:29], v[28:29], v[60:61] op_sel_hi:[1,0]
	global_store_dwordx4 v[56:57], v[34:37], off
	v_pk_mul_f32 v[32:33], v[16:17], v[32:33]
	v_pk_mul_f32 v[30:31], v[14:15], v[30:31]
	v_pk_mul_f32 v[34:35], v[12:13], v[28:29]
	v_pk_mul_f32 v[28:29], v[10:11], v[26:27]
	v_cvt_pk_bf16_f32 v26, v30, v31
	v_cvt_pk_bf16_f32 v27, v32, v33
	v_cvt_pk_bf16_f32 v28, v28, v29
	v_cvt_pk_bf16_f32 v29, v34, v35
	global_store_dwordx4 v[54:55], v[26:29], off offset:1024
	v_pk_mul_f32 v[22:23], v[22:23], v[58:59] op_sel_hi:[1,0]
	v_pk_mul_f32 v[24:25], v[24:25], v[58:59] op_sel_hi:[1,0]
	v_pk_mul_f32 v[18:19], v[18:19], v[58:59] op_sel_hi:[1,0]
	v_pk_mul_f32 v[20:21], v[20:21], v[58:59] op_sel_hi:[1,0]
	v_pk_mul_f32 v[24:25], v[16:17], v[24:25]
	v_pk_mul_f32 v[22:23], v[14:15], v[22:23]
	v_pk_mul_f32 v[26:27], v[12:13], v[20:21]
	v_pk_mul_f32 v[20:21], v[10:11], v[18:19]
	v_cvt_pk_bf16_f32 v18, v22, v23
	v_cvt_pk_bf16_f32 v19, v24, v25
	v_cvt_pk_bf16_f32 v20, v20, v21
	v_cvt_pk_bf16_f32 v21, v26, v27
	global_store_dwordx4 v[56:57], v[18:21], off offset:1024
.Ln2_loop:
	s_add_i32 s0, s1, s8
	s_cmp_lt_i32 s0, s49
	s_cbranch_scc0 .Ln2_lastB
	s_add_i32 s9, s0, s24
	s_cmp_lt_i32 s9, s49
	s_cselect_b32 s9, s9, s0
	s_lshl_b32 s10, s0, 12
	s_lshl_b32 s4, s9, 12
	v_mov_b32_e32 v62, s10
	v_mov_b32_e32 v63, 0
	v_lshl_add_u64 v[58:59], v[50:51], 0, v[62:63]
	v_mov_b32_e32 v62, s4
	v_lshl_add_u64 v[60:61], v[50:51], 0, v[62:63]
	global_load_dwordx4 v[46:49], v[58:59], off
	global_load_dwordx4 v[42:45], v[58:59], off offset:16
	global_load_dwordx4 v[38:41], v[60:61], off
	global_load_dwordx4 v[34:37], v[60:61], off offset:16
	global_load_dwordx4 v[30:33], v[58:59], off offset:2048
	global_load_dwordx4 v[26:29], v[58:59], off offset:2064
	global_load_dwordx4 v[22:25], v[60:61], off offset:2048
	global_load_dwordx4 v[18:21], v[60:61], off offset:2064
	s_lshl_b32 s10, s0, 11
	s_lshl_b32 s4, s9, 11
	v_mov_b32_e32 v62, s10
	v_lshl_add_u64 v[54:55], v[52:53], 0, v[62:63]
	v_mov_b32_e32 v62, s4
	v_lshl_add_u64 v[56:57], v[52:53], 0, v[62:63]
	s_waitcnt vmcnt(12)
	v_mov_b32_e32 v60, v101
	v_mov_b32_e32 v61, v97
	v_mov_b32_e32 v58, v100
	v_mov_b32_e32 v59, v96
	v_pk_mul_f32 v[60:61], v[60:61], v[60:61]
	v_mov_b32_e32 v62, v93
	v_pk_fma_f32 v[58:59], v[58:59], v[58:59], v[60:61]
	v_mov_b32_e32 v60, v102
	v_mov_b32_e32 v61, v98
	v_pk_fma_f32 v[58:59], v[60:61], v[60:61], v[58:59]
	v_mov_b32_e32 v60, v103
	v_mov_b32_e32 v61, v99
	v_mov_b32_e32 v63, v89
	v_pk_fma_f32 v[58:59], v[60:61], v[60:61], v[58:59]
	v_mov_b32_e32 v60, v92
	v_mov_b32_e32 v61, v88
	v_pk_mul_f32 v[62:63], v[62:63], v[62:63]
	v_mov_b32_e32 v64, v83
	v_pk_fma_f32 v[60:61], v[60:61], v[60:61], v[62:63]
	v_mov_b32_e32 v62, v94
	v_mov_b32_e32 v63, v90
	v_pk_fma_f32 v[60:61], v[62:63], v[62:63], v[60:61]
	v_mov_b32_e32 v62, v95
	v_mov_b32_e32 v63, v91
	v_mov_b32_e32 v65, v79
	v_pk_fma_f32 v[60:61], v[62:63], v[62:63], v[60:61]
	v_mov_b32_e32 v62, v82
	v_mov_b32_e32 v63, v78
	v_pk_mul_f32 v[64:65], v[64:65], v[64:65]
	v_mov_b32_e32 v66, v75
	v_pk_fma_f32 v[62:63], v[62:63], v[62:63], v[64:65]
	v_mov_b32_e32 v64, v84
	v_mov_b32_e32 v65, v80
	v_pk_fma_f32 v[62:63], v[64:65], v[64:65], v[62:63]
	v_mov_b32_e32 v64, v85
	v_mov_b32_e32 v65, v81
	v_mov_b32_e32 v67, v71
	v_pk_fma_f32 v[62:63], v[64:65], v[64:65], v[62:63]
	v_mov_b32_e32 v64, v74
	v_mov_b32_e32 v65, v70
	v_pk_mul_f32 v[66:67], v[66:67], v[66:67]
	s_nop 0
	v_pk_fma_f32 v[64:65], v[64:65], v[64:65], v[66:67]
	v_mov_b32_e32 v66, v76
	v_mov_b32_e32 v67, v72
	v_pk_fma_f32 v[64:65], v[66:67], v[66:67], v[64:65]
	v_mov_b32_e32 v66, v77
	v_mov_b32_e32 v67, v73
	v_pk_fma_f32 v[64:65], v[66:67], v[66:67], v[64:65]
	v_mov_b32_e32 v66, v210
	v_mov_b32_e32 v67, v58
	v_lshlrev_b32_e32 v66, 2, v66
	v_xor_b32_e32 v68, 0x80, v66
	v_mov_b32_e32 v66, v210
	v_mov_b32_e32 v58, v61
	v_lshlrev_b32_e32 v66, 2, v66
	v_xor_b32_e32 v69, 0x80, v66
	v_mov_b32_e32 v66, v60
	v_pk_add_f32 v[58:59], v[66:67], v[58:59]
	v_mov_b32_e32 v60, v64
	v_mov_b32_e32 v61, v62
	v_pk_add_f32 v[58:59], v[58:59], v[60:61]
	v_mov_b32_e32 v62, v65
	v_pk_add_f32 v[58:59], v[58:59], v[62:63]
	ds_swizzle_b32 v61, v59 offset:swizzle(SWAP,16)
	ds_swizzle_b32 v60, v58 offset:swizzle(SWAP,16)
	s_waitcnt lgkmcnt(0)
; __device__ __forceinline__ void store8bf(bf16_t* p, f32x4 v0, f32x4 v1) { u32x4 w; w.x = cvt_pk_bf16(v0[0], v0[1]); w.y = cvt_pk_bf16(v0[2], v0[3]); w.z = cvt_pk_bf16(v1[0], v1[1]); w.w = cvt_pk_bf16(v1[2], v1[3]); *(u32x4*)p = w; }
; __device__ __forceinline__ void norm_phase(const float* H, const float* g, bf16_t* HN) {
;     ...
;   for (int row = gw; row < NREAL + 64; row += 2 * nw) {
;     const int row2 = row + nw < NREAL + 64 ? row + nw : row;
;     const float* p = H + (size_t)row * DM + lane * 8; const float* p2 = H + (size_t)row2 * DM + lane * 8; f32x4 v[4], u[4]; float ss = 0.f, ss2 = 0.f;
; #pragma unroll
;     for (int i = 0; i < 4; ++i) { v[i] = *(const f32x4*)(p + 512 * (i >> 1) + 4 * (i & 1)); u[i] = *(const f32x4*)(p2 + 512 * (i >> 1) + 4 * (i & 1)); }
;     ...
;     ss = wave_sum(ss); ss2 = wave_sum(ss2); const float rs = rsqrtf(ss * (1.0f / 1024.0f) + 1e-6f), rs2 = rsqrtf(ss2 * (1.0f / 1024.0f) + 1e-6f);
;     bf16_t* q = HN + (size_t)row * DM + lane * 8; bf16_t* q2 = HN + (size_t)row2 * DM + lane * 8;
; #pragma unroll
;     for (int i = 0; i < 2; ++i) { store8bf(q + 512 * i, v[2 * i] * rs * gv[2 * i], v[2 * i + 1] * rs * gv[2 * i + 1]); store8bf(q2 + 512 * i, u[2 * i] * rs2 * gv[2 * i], u[2 * i + 1] * rs2 * gv[2 * i + 1]); }
;   }
	v_pk_add_f32 v[58:59], v[58:59], v[60:61]
	ds_swizzle_b32 v61, v59 offset:swizzle(SWAP,8)
	ds_swizzle_b32 v60, v58 offset:swizzle(SWAP,8)
	s_waitcnt lgkmcnt(0)
	v_pk_add_f32 v[58:59], v[58:59], v[60:61]
	ds_swizzle_b32 v61, v59 offset:swizzle(SWAP,4)
	ds_swizzle_b32 v60, v58 offset:swizzle(SWAP,4)
	s_waitcnt lgkmcnt(0)
	v_pk_add_f32 v[58:59], v[58:59], v[60:61]
	ds_swizzle_b32 v61, v59 offset:swizzle(SWAP,2)
	ds_swizzle_b32 v60, v58 offset:swizzle(SWAP,2)
	s_waitcnt lgkmcnt(0)
	v_pk_add_f32 v[58:59], v[58:59], v[60:61]
	ds_swizzle_b32 v61, v59 offset:swizzle(SWAP,1)
	ds_swizzle_b32 v60, v58 offset:swizzle(SWAP,1)
	s_waitcnt lgkmcnt(0)
	v_pk_add_f32 v[58:59], v[58:59], v[60:61]
	ds_bpermute_b32 v61, v68, v59
	ds_bpermute_b32 v60, v69, v58
	s_waitcnt lgkmcnt(0)
	v_pk_add_f32 v[58:59], v[58:59], v[60:61]
	s_nop 0
	v_pk_fma_f32 v[58:59], v[58:59], s[58:59], v[154:155] op_sel_hi:[1,0,0]
	s_nop 0
	v_mul_f32_e32 v60, 0x4b800000, v59
	v_cmp_gt_f32_e64 s[4:5], s46, v59
	v_cmp_gt_f32_e32 vcc, s46, v58
	s_nop 0
	v_cndmask_b32_e64 v59, v59, v60, s[4:5]
	v_rsq_f32_e32 v59, v59
	s_nop 0
	v_mul_f32_e32 v60, 0x45800000, v59
	v_cndmask_b32_e64 v60, v59, v60, s[4:5]
	v_mul_f32_e32 v59, 0x4b800000, v58
	v_cndmask_b32_e32 v58, v58, v59, vcc
	v_rsq_f32_e32 v58, v58
	v_pk_mul_f32 v[100:101], v[100:101], v[60:61] op_sel_hi:[1,0]
	v_pk_mul_f32 v[102:103], v[102:103], v[60:61] op_sel_hi:[1,0]
	v_pk_mul_f32 v[96:97], v[96:97], v[60:61] op_sel_hi:[1,0]
	v_mul_f32_e32 v59, 0x45800000, v58
	v_pk_mul_f32 v[98:99], v[98:99], v[60:61] op_sel_hi:[1,0]
	v_cndmask_b32_e32 v58, v58, v59, vcc
	v_pk_mul_f32 v[102:103], v[8:9], v[102:103]
	v_pk_mul_f32 v[100:101], v[6:7], v[100:101]
	v_pk_mul_f32 v[62:63], v[4:5], v[98:99]
	v_pk_mul_f32 v[98:99], v[2:3], v[96:97]
	v_cvt_pk_bf16_f32 v96, v100, v101
	v_cvt_pk_bf16_f32 v97, v102, v103
	v_cvt_pk_bf16_f32 v98, v98, v99
	v_cvt_pk_bf16_f32 v99, v62, v63
	v_pk_mul_f32 v[92:93], v[92:93], v[58:59] op_sel_hi:[1,0]
	v_pk_mul_f32 v[94:95], v[94:95], v[58:59] op_sel_hi:[1,0]
	v_pk_mul_f32 v[88:89], v[88:89], v[58:59] op_sel_hi:[1,0]
	v_pk_mul_f32 v[90:91], v[90:91], v[58:59] op_sel_hi:[1,0]
	global_store_dwordx4 v[128:129], v[96:99], off
	v_pk_mul_f32 v[94:95], v[8:9], v[94:95]
	v_pk_mul_f32 v[92:93], v[6:7], v[92:93]
	v_pk_mul_f32 v[96:97], v[4:5], v[90:91]
	v_pk_mul_f32 v[90:91], v[2:3], v[88:89]
	v_cvt_pk_bf16_f32 v88, v92, v93
	v_cvt_pk_bf16_f32 v89, v94, v95
	v_cvt_pk_bf16_f32 v90, v90, v91
	v_cvt_pk_bf16_f32 v91, v96, v97
	v_pk_mul_f32 v[82:83], v[82:83], v[60:61] op_sel_hi:[1,0]
	v_pk_mul_f32 v[84:85], v[84:85], v[60:61] op_sel_hi:[1,0]
	v_pk_mul_f32 v[78:79], v[78:79], v[60:61] op_sel_hi:[1,0]
	v_pk_mul_f32 v[80:81], v[80:81], v[60:61] op_sel_hi:[1,0]
	global_store_dwordx4 v[130:131], v[88:91], off
	v_pk_mul_f32 v[84:85], v[16:17], v[84:85]
	v_pk_mul_f32 v[82:83], v[14:15], v[82:83]
	v_pk_mul_f32 v[88:89], v[12:13], v[80:81]
	v_pk_mul_f32 v[80:81], v[10:11], v[78:79]
	v_cvt_pk_bf16_f32 v78, v82, v83
	v_cvt_pk_bf16_f32 v79, v84, v85
	v_cvt_pk_bf16_f32 v80, v80, v81
	v_cvt_pk_bf16_f32 v81, v88, v89
	global_store_dwordx4 v[128:129], v[78:81], off offset:1024
	v_pk_mul_f32 v[74:75], v[74:75], v[58:59] op_sel_hi:[1,0]
	v_pk_mul_f32 v[76:77], v[76:77], v[58:59] op_sel_hi:[1,0]
	v_pk_mul_f32 v[70:71], v[70:71], v[58:59] op_sel_hi:[1,0]
	v_pk_mul_f32 v[72:73], v[72:73], v[58:59] op_sel_hi:[1,0]
	v_pk_mul_f32 v[76:77], v[16:17], v[76:77]
	v_pk_mul_f32 v[74:75], v[14:15], v[74:75]
	v_pk_mul_f32 v[78:79], v[12:13], v[72:73]
	v_pk_mul_f32 v[72:73], v[10:11], v[70:71]
	v_cvt_pk_bf16_f32 v70, v74, v75
	v_cvt_pk_bf16_f32 v71, v76, v77
	v_cvt_pk_bf16_f32 v72, v72, v73
	v_cvt_pk_bf16_f32 v73, v78, v79
	global_store_dwordx4 v[130:131], v[70:73], off offset:1024
	s_add_i32 s1, s0, s8
	s_cmp_lt_i32 s1, s49
	s_cbranch_scc0 .Ln2_lastA
	s_add_i32 s9, s1, s24
	s_cmp_lt_i32 s9, s49
	s_cselect_b32 s9, s9, s1
	s_lshl_b32 s10, s1, 12
	s_lshl_b32 s4, s9, 12
	v_mov_b32_e32 v62, s10
	v_mov_b32_e32 v63, 0
	v_lshl_add_u64 v[58:59], v[50:51], 0, v[62:63]
	v_mov_b32_e32 v62, s4
	v_lshl_add_u64 v[60:61], v[50:51], 0, v[62:63]
	global_load_dwordx4 v[100:103], v[58:59], off
	global_load_dwordx4 v[96:99], v[58:59], off offset:16
	global_load_dwordx4 v[92:95], v[60:61], off
	global_load_dwordx4 v[88:91], v[60:61], off offset:16
	global_load_dwordx4 v[82:85], v[58:59], off offset:2048
	global_load_dwordx4 v[78:81], v[58:59], off offset:2064
	global_load_dwordx4 v[74:77], v[60:61], off offset:2048
	global_load_dwordx4 v[70:73], v[60:61], off offset:2064
	s_lshl_b32 s10, s1, 11
	s_lshl_b32 s4, s9, 11
	v_mov_b32_e32 v62, s10
	v_lshl_add_u64 v[128:129], v[52:53], 0, v[62:63]
	v_mov_b32_e32 v62, s4
	v_lshl_add_u64 v[130:131], v[52:53], 0, v[62:63]
	s_waitcnt vmcnt(12)
; __device__ __forceinline__ void store8bf(bf16_t* p, f32x4 v0, f32x4 v1) { u32x4 w; w.x = cvt_pk_bf16(v0[0], v0[1]); w.y = cvt_pk_bf16(v0[2], v0[3]); w.z = cvt_pk_bf16(v1[0], v1[1]); w.w = cvt_pk_bf16(v1[2], v1[3]); *(u32x4*)p = w; }
; __device__ __forceinline__ void norm_phase(const float* H, const float* g, bf16_t* HN) {
;     ...
;     const float* p = H + (size_t)row * DM + lane * 8; const float* p2 = H + (size_t)row2 * DM + lane * 8; f32x4 v[4], u[4]; float ss = 0.f, ss2 = 0.f;
; #pragma unroll
;     for (int i = 0; i < 4; ++i) { v[i] = *(const f32x4*)(p + 512 * (i >> 1) + 4 * (i & 1)); u[i] = *(const f32x4*)(p2 + 512 * (i >> 1) + 4 * (i & 1)); }
; #pragma unroll
;     for (int i = 0; i < 4; ++i) { ss += v[i][0] * v[i][0] + v[i][1] * v[i][1] + v[i][2] * v[i][2] + v[i][3] * v[i][3]; ss2 += u[i][0] * u[i][0] + u[i][1] * u[i][1] + u[i][2] * u[i][2] + u[i][3] * u[i][3]; }
;     ss = wave_sum(ss); ss2 = wave_sum(ss2); const float rs = rsqrtf(ss * (1.0f / 1024.0f) + 1e-6f), rs2 = rsqrtf(ss2 * (1.0f / 1024.0f) + 1e-6f);
;     bf16_t* q = HN + (size_t)row * DM + lane * 8; bf16_t* q2 = HN + (size_t)row2 * DM + lane * 8;
; #pragma unroll
;     for (int i = 0; i < 2; ++i) { store8bf(q + 512 * i, v[2 * i] * rs * gv[2 * i], v[2 * i + 1] * rs * gv[2 * i + 1]); store8bf(q2 + 512 * i, u[2 * i] * rs2 * gv[2 * i], u[2 * i + 1] * rs2 * gv[2 * i + 1]); }
	v_mov_b32_e32 v60, v47
	v_mov_b32_e32 v61, v43
	v_mov_b32_e32 v58, v46
	v_mov_b32_e32 v59, v42
	v_pk_mul_f32 v[60:61], v[60:61], v[60:61]
	v_mov_b32_e32 v62, v39
	v_pk_fma_f32 v[58:59], v[58:59], v[58:59], v[60:61]
	v_mov_b32_e32 v60, v48
	v_mov_b32_e32 v61, v44
	v_pk_fma_f32 v[58:59], v[60:61], v[60:61], v[58:59]
	v_mov_b32_e32 v60, v49
	v_mov_b32_e32 v61, v45
	v_mov_b32_e32 v63, v35
	v_pk_fma_f32 v[58:59], v[60:61], v[60:61], v[58:59]
	v_mov_b32_e32 v60, v38
	v_mov_b32_e32 v61, v34
	v_pk_mul_f32 v[62:63], v[62:63], v[62:63]
	v_mov_b32_e32 v64, v31
	v_pk_fma_f32 v[60:61], v[60:61], v[60:61], v[62:63]
	v_mov_b32_e32 v62, v40
	v_mov_b32_e32 v63, v36
	v_pk_fma_f32 v[60:61], v[62:63], v[62:63], v[60:61]
	v_mov_b32_e32 v62, v41
	v_mov_b32_e32 v63, v37
	v_mov_b32_e32 v65, v27
	v_pk_fma_f32 v[60:61], v[62:63], v[62:63], v[60:61]
	v_mov_b32_e32 v62, v30
	v_mov_b32_e32 v63, v26
	v_pk_mul_f32 v[64:65], v[64:65], v[64:65]
	v_mov_b32_e32 v66, v23
	v_pk_fma_f32 v[62:63], v[62:63], v[62:63], v[64:65]
	v_mov_b32_e32 v64, v32
	v_mov_b32_e32 v65, v28
	v_pk_fma_f32 v[62:63], v[64:65], v[64:65], v[62:63]
	v_mov_b32_e32 v64, v33
	v_mov_b32_e32 v65, v29
	v_mov_b32_e32 v67, v19
	v_pk_fma_f32 v[62:63], v[64:65], v[64:65], v[62:63]
	v_mov_b32_e32 v64, v22
	v_mov_b32_e32 v65, v18
	v_pk_mul_f32 v[66:67], v[66:67], v[66:67]
	s_nop 0
	v_pk_fma_f32 v[64:65], v[64:65], v[64:65], v[66:67]
	v_mov_b32_e32 v66, v24
	v_mov_b32_e32 v67, v20
	v_pk_fma_f32 v[64:65], v[66:67], v[66:67], v[64:65]
	v_mov_b32_e32 v66, v25
	v_mov_b32_e32 v67, v21
	v_pk_fma_f32 v[64:65], v[66:67], v[66:67], v[64:65]
	v_mov_b32_e32 v66, v210
	v_mov_b32_e32 v67, v58
	v_lshlrev_b32_e32 v66, 2, v66
	v_xor_b32_e32 v68, 0x80, v66
	v_mov_b32_e32 v66, v210
	v_mov_b32_e32 v58, v61
	v_lshlrev_b32_e32 v66, 2, v66
	v_xor_b32_e32 v69, 0x80, v66
	v_mov_b32_e32 v66, v60
	v_pk_add_f32 v[58:59], v[66:67], v[58:59]
	v_mov_b32_e32 v60, v64
	v_mov_b32_e32 v61, v62
	v_pk_add_f32 v[58:59], v[58:59], v[60:61]
	v_mov_b32_e32 v62, v65
	v_pk_add_f32 v[58:59], v[58:59], v[62:63]
	ds_swizzle_b32 v61, v59 offset:swizzle(SWAP,16)
	ds_swizzle_b32 v60, v58 offset:swizzle(SWAP,16)
	s_waitcnt lgkmcnt(0)
	v_pk_add_f32 v[58:59], v[58:59], v[60:61]
	ds_swizzle_b32 v61, v59 offset:swizzle(SWAP,8)
	ds_swizzle_b32 v60, v58 offset:swizzle(SWAP,8)
	s_waitcnt lgkmcnt(0)
	v_pk_add_f32 v[58:59], v[58:59], v[60:61]
	ds_swizzle_b32 v61, v59 offset:swizzle(SWAP,4)
	ds_swizzle_b32 v60, v58 offset:swizzle(SWAP,4)
	s_waitcnt lgkmcnt(0)
	v_pk_add_f32 v[58:59], v[58:59], v[60:61]
	ds_swizzle_b32 v61, v59 offset:swizzle(SWAP,2)
	ds_swizzle_b32 v60, v58 offset:swizzle(SWAP,2)
	s_waitcnt lgkmcnt(0)
	v_pk_add_f32 v[58:59], v[58:59], v[60:61]
	ds_swizzle_b32 v61, v59 offset:swizzle(SWAP,1)
	ds_swizzle_b32 v60, v58 offset:swizzle(SWAP,1)
	s_waitcnt lgkmcnt(0)
	v_pk_add_f32 v[58:59], v[58:59], v[60:61]
	ds_bpermute_b32 v61, v68, v59
	ds_bpermute_b32 v60, v69, v58
	s_waitcnt lgkmcnt(0)
	v_pk_add_f32 v[58:59], v[58:59], v[60:61]
	s_nop 0
	v_pk_fma_f32 v[58:59], v[58:59], s[58:59], v[154:155] op_sel_hi:[1,0,0]
	s_nop 0
	v_mul_f32_e32 v60, 0x4b800000, v59
	v_cmp_gt_f32_e64 s[4:5], s46, v59
	v_cmp_gt_f32_e32 vcc, s46, v58
	s_nop 0
	v_cndmask_b32_e64 v59, v59, v60, s[4:5]
	v_rsq_f32_e32 v59, v59
	s_nop 0
	v_mul_f32_e32 v60, 0x45800000, v59
	v_cndmask_b32_e64 v60, v59, v60, s[4:5]
	v_mul_f32_e32 v59, 0x4b800000, v58
	v_cndmask_b32_e32 v58, v58, v59, vcc
	v_rsq_f32_e32 v58, v58
	v_pk_mul_f32 v[46:47], v[46:47], v[60:61] op_sel_hi:[1,0]
	v_pk_mul_f32 v[48:49], v[48:49], v[60:61] op_sel_hi:[1,0]
	v_pk_mul_f32 v[42:43], v[42:43], v[60:61] op_sel_hi:[1,0]
	v_mul_f32_e32 v59, 0x45800000, v58
	v_pk_mul_f32 v[44:45], v[44:45], v[60:61] op_sel_hi:[1,0]
	v_cndmask_b32_e32 v58, v58, v59, vcc
	v_pk_mul_f32 v[48:49], v[8:9], v[48:49]
	v_pk_mul_f32 v[46:47], v[6:7], v[46:47]
	v_pk_mul_f32 v[62:63], v[4:5], v[44:45]
	v_pk_mul_f32 v[44:45], v[2:3], v[42:43]
	v_cvt_pk_bf16_f32 v42, v46, v47
	v_cvt_pk_bf16_f32 v43, v48, v49
	v_cvt_pk_bf16_f32 v44, v44, v45
	v_cvt_pk_bf16_f32 v45, v62, v63
	v_pk_mul_f32 v[38:39], v[38:39], v[58:59] op_sel_hi:[1,0]
	v_pk_mul_f32 v[40:41], v[40:41], v[58:59] op_sel_hi:[1,0]
	v_pk_mul_f32 v[34:35], v[34:35], v[58:59] op_sel_hi:[1,0]
	v_pk_mul_f32 v[36:37], v[36:37], v[58:59] op_sel_hi:[1,0]
	global_store_dwordx4 v[54:55], v[42:45], off
	v_pk_mul_f32 v[40:41], v[8:9], v[40:41]
	v_pk_mul_f32 v[38:39], v[6:7], v[38:39]
	v_pk_mul_f32 v[42:43], v[4:5], v[36:37]
	v_pk_mul_f32 v[36:37], v[2:3], v[34:35]
	v_cvt_pk_bf16_f32 v34, v38, v39
	v_cvt_pk_bf16_f32 v35, v40, v41
	v_cvt_pk_bf16_f32 v36, v36, v37
	v_cvt_pk_bf16_f32 v37, v42, v43
	v_pk_mul_f32 v[30:31], v[30:31], v[60:61] op_sel_hi:[1,0]
	v_pk_mul_f32 v[32:33], v[32:33], v[60:61] op_sel_hi:[1,0]
	v_pk_mul_f32 v[26:27], v[26:27], v[60:61] op_sel_hi:[1,0]
	v_pk_mul_f32 v[28:29], v[28:29], v[60:61] op_sel_hi:[1,0]
	global_store_dwordx4 v[56:57], v[34:37], off
	v_pk_mul_f32 v[32:33], v[16:17], v[32:33]
	v_pk_mul_f32 v[30:31], v[14:15], v[30:31]
	v_pk_mul_f32 v[34:35], v[12:13], v[28:29]
	v_pk_mul_f32 v[28:29], v[10:11], v[26:27]
	v_cvt_pk_bf16_f32 v26, v30, v31
	v_cvt_pk_bf16_f32 v27, v32, v33
	v_cvt_pk_bf16_f32 v28, v28, v29
	v_cvt_pk_bf16_f32 v29, v34, v35
	global_store_dwordx4 v[54:55], v[26:29], off offset:1024
	v_pk_mul_f32 v[22:23], v[22:23], v[58:59] op_sel_hi:[1,0]
	v_pk_mul_f32 v[24:25], v[24:25], v[58:59] op_sel_hi:[1,0]
	v_pk_mul_f32 v[18:19], v[18:19], v[58:59] op_sel_hi:[1,0]
	v_pk_mul_f32 v[20:21], v[20:21], v[58:59] op_sel_hi:[1,0]
	v_pk_mul_f32 v[24:25], v[16:17], v[24:25]
	v_pk_mul_f32 v[22:23], v[14:15], v[22:23]
	v_pk_mul_f32 v[26:27], v[12:13], v[20:21]
	v_pk_mul_f32 v[20:21], v[10:11], v[18:19]
	v_cvt_pk_bf16_f32 v18, v22, v23
	v_cvt_pk_bf16_f32 v19, v24, v25
	v_cvt_pk_bf16_f32 v20, v20, v21
	v_cvt_pk_bf16_f32 v21, v26, v27
	global_store_dwordx4 v[56:57], v[18:21], off offset:1024
	s_branch .Ln2_loop
; __device__ __forceinline__ void store8bf(bf16_t* p, f32x4 v0, f32x4 v1) { u32x4 w; w.x = cvt_pk_bf16(v0[0], v0[1]); w.y = cvt_pk_bf16(v0[2], v0[3]); w.z = cvt_pk_bf16(v1[0], v1[1]); w.w = cvt_pk_bf16(v1[2], v1[3]); *(u32x4*)p = w; }
; __device__ __forceinline__ void norm_phase(const float* H, const float* g, bf16_t* HN) {
;     ...
;     const float* p = H + (size_t)row * DM + lane * 8; const float* p2 = H + (size_t)row2 * DM + lane * 8; f32x4 v[4], u[4]; float ss = 0.f, ss2 = 0.f;
; #pragma unroll
;     for (int i = 0; i < 4; ++i) { v[i] = *(const f32x4*)(p + 512 * (i >> 1) + 4 * (i & 1)); u[i] = *(const f32x4*)(p2 + 512 * (i >> 1) + 4 * (i & 1)); }
; #pragma unroll
;     for (int i = 0; i < 4; ++i) { ss += v[i][0] * v[i][0] + v[i][1] * v[i][1] + v[i][2] * v[i][2] + v[i][3] * v[i][3]; ss2 += u[i][0] * u[i][0] + u[i][1] * u[i][1] + u[i][2] * u[i][2] + u[i][3] * u[i][3]; }
;     ss = wave_sum(ss); ss2 = wave_sum(ss2); const float rs = rsqrtf(ss * (1.0f / 1024.0f) + 1e-6f), rs2 = rsqrtf(ss2 * (1.0f / 1024.0f) + 1e-6f);
;     bf16_t* q = HN + (size_t)row * DM + lane * 8; bf16_t* q2 = HN + (size_t)row2 * DM + lane * 8;
; #pragma unroll
;     for (int i = 0; i < 2; ++i) { store8bf(q + 512 * i, v[2 * i] * rs * gv[2 * i], v[2 * i + 1] * rs * gv[2 * i + 1]); store8bf(q2 + 512 * i, u[2 * i] * rs2 * gv[2 * i], u[2 * i + 1] * rs2 * gv[2 * i + 1]); }
.Ln2_lastA_first:
	s_waitcnt vmcnt(0)
	v_mov_b32_e32 v60, v47
	v_mov_b32_e32 v61, v43
	v_mov_b32_e32 v58, v46
	v_mov_b32_e32 v59, v42
	v_pk_mul_f32 v[60:61], v[60:61], v[60:61]
	v_mov_b32_e32 v62, v39
	v_pk_fma_f32 v[58:59], v[58:59], v[58:59], v[60:61]
	v_mov_b32_e32 v60, v48
	v_mov_b32_e32 v61, v44
	v_pk_fma_f32 v[58:59], v[60:61], v[60:61], v[58:59]
	v_mov_b32_e32 v60, v49
	v_mov_b32_e32 v61, v45
	v_mov_b32_e32 v63, v35
	v_pk_fma_f32 v[58:59], v[60:61], v[60:61], v[58:59]
	v_mov_b32_e32 v60, v38
	v_mov_b32_e32 v61, v34
	v_pk_mul_f32 v[62:63], v[62:63], v[62:63]
	v_mov_b32_e32 v64, v31
	v_pk_fma_f32 v[60:61], v[60:61], v[60:61], v[62:63]
	v_mov_b32_e32 v62, v40
	v_mov_b32_e32 v63, v36
	v_pk_fma_f32 v[60:61], v[62:63], v[62:63], v[60:61]
	v_mov_b32_e32 v62, v41
	v_mov_b32_e32 v63, v37
	v_mov_b32_e32 v65, v27
	v_pk_fma_f32 v[60:61], v[62:63], v[62:63], v[60:61]
	v_mov_b32_e32 v62, v30
	v_mov_b32_e32 v63, v26
	v_pk_mul_f32 v[64:65], v[64:65], v[64:65]
	v_mov_b32_e32 v66, v23
	v_pk_fma_f32 v[62:63], v[62:63], v[62:63], v[64:65]
	v_mov_b32_e32 v64, v32
	v_mov_b32_e32 v65, v28
	v_pk_fma_f32 v[62:63], v[64:65], v[64:65], v[62:63]
	v_mov_b32_e32 v64, v33
	v_mov_b32_e32 v65, v29
	v_mov_b32_e32 v67, v19
	v_pk_fma_f32 v[62:63], v[64:65], v[64:65], v[62:63]
	v_mov_b32_e32 v64, v22
	v_mov_b32_e32 v65, v18
	v_pk_mul_f32 v[66:67], v[66:67], v[66:67]
	s_nop 0
	v_pk_fma_f32 v[64:65], v[64:65], v[64:65], v[66:67]
	v_mov_b32_e32 v66, v24
	v_mov_b32_e32 v67, v20
	v_pk_fma_f32 v[64:65], v[66:67], v[66:67], v[64:65]
	v_mov_b32_e32 v66, v25
	v_mov_b32_e32 v67, v21
	v_pk_fma_f32 v[64:65], v[66:67], v[66:67], v[64:65]
	v_mov_b32_e32 v66, v210
	v_mov_b32_e32 v67, v58
	v_lshlrev_b32_e32 v66, 2, v66
	v_xor_b32_e32 v68, 0x80, v66
	v_mov_b32_e32 v66, v210
	v_mov_b32_e32 v58, v61
	v_lshlrev_b32_e32 v66, 2, v66
	v_xor_b32_e32 v69, 0x80, v66
	v_mov_b32_e32 v66, v60
	v_pk_add_f32 v[58:59], v[66:67], v[58:59]
	v_mov_b32_e32 v60, v64
	v_mov_b32_e32 v61, v62
	v_pk_add_f32 v[58:59], v[58:59], v[60:61]
	v_mov_b32_e32 v62, v65
	v_pk_add_f32 v[58:59], v[58:59], v[62:63]
	ds_swizzle_b32 v61, v59 offset:swizzle(SWAP,16)
	ds_swizzle_b32 v60, v58 offset:swizzle(SWAP,16)
	s_waitcnt lgkmcnt(0)
	v_pk_add_f32 v[58:59], v[58:59], v[60:61]
	ds_swizzle_b32 v61, v59 offset:swizzle(SWAP,8)
	ds_swizzle_b32 v60, v58 offset:swizzle(SWAP,8)
	s_waitcnt lgkmcnt(0)
	v_pk_add_f32 v[58:59], v[58:59], v[60:61]
	ds_swizzle_b32 v61, v59 offset:swizzle(SWAP,4)
	ds_swizzle_b32 v60, v58 offset:swizzle(SWAP,4)
	s_waitcnt lgkmcnt(0)
	v_pk_add_f32 v[58:59], v[58:59], v[60:61]
	ds_swizzle_b32 v61, v59 offset:swizzle(SWAP,2)
	ds_swizzle_b32 v60, v58 offset:swizzle(SWAP,2)
	s_waitcnt lgkmcnt(0)
	v_pk_add_f32 v[58:59], v[58:59], v[60:61]
	ds_swizzle_b32 v61, v59 offset:swizzle(SWAP,1)
	ds_swizzle_b32 v60, v58 offset:swizzle(SWAP,1)
	s_waitcnt lgkmcnt(0)
	v_pk_add_f32 v[58:59], v[58:59], v[60:61]
	ds_bpermute_b32 v61, v68, v59
	ds_bpermute_b32 v60, v69, v58
	s_waitcnt lgkmcnt(0)
	v_pk_add_f32 v[58:59], v[58:59], v[60:61]
	s_nop 0
	v_pk_fma_f32 v[58:59], v[58:59], s[58:59], v[154:155] op_sel_hi:[1,0,0]
	s_nop 0
	v_mul_f32_e32 v60, 0x4b800000, v59
	v_cmp_gt_f32_e64 s[4:5], s46, v59
	v_cmp_gt_f32_e32 vcc, s46, v58
	s_nop 0
	v_cndmask_b32_e64 v59, v59, v60, s[4:5]
	v_rsq_f32_e32 v59, v59
	s_nop 0
	v_mul_f32_e32 v60, 0x45800000, v59
	v_cndmask_b32_e64 v60, v59, v60, s[4:5]
	v_mul_f32_e32 v59, 0x4b800000, v58
	v_cndmask_b32_e32 v58, v58, v59, vcc
	v_rsq_f32_e32 v58, v58
	v_pk_mul_f32 v[46:47], v[46:47], v[60:61] op_sel_hi:[1,0]
	v_pk_mul_f32 v[48:49], v[48:49], v[60:61] op_sel_hi:[1,0]
	v_pk_mul_f32 v[42:43], v[42:43], v[60:61] op_sel_hi:[1,0]
	v_mul_f32_e32 v59, 0x45800000, v58
	v_pk_mul_f32 v[44:45], v[44:45], v[60:61] op_sel_hi:[1,0]
	v_cndmask_b32_e32 v58, v58, v59, vcc
	v_pk_mul_f32 v[48:49], v[8:9], v[48:49]
	v_pk_mul_f32 v[46:47], v[6:7], v[46:47]
	v_pk_mul_f32 v[62:63], v[4:5], v[44:45]
	v_pk_mul_f32 v[44:45], v[2:3], v[42:43]
	v_cvt_pk_bf16_f32 v42, v46, v47
	v_cvt_pk_bf16_f32 v43, v48, v49
	v_cvt_pk_bf16_f32 v44, v44, v45
	v_cvt_pk_bf16_f32 v45, v62, v63
	v_pk_mul_f32 v[38:39], v[38:39], v[58:59] op_sel_hi:[1,0]
	v_pk_mul_f32 v[40:41], v[40:41], v[58:59] op_sel_hi:[1,0]
	v_pk_mul_f32 v[34:35], v[34:35], v[58:59] op_sel_hi:[1,0]
	v_pk_mul_f32 v[36:37], v[36:37], v[58:59] op_sel_hi:[1,0]
	global_store_dwordx4 v[54:55], v[42:45], off
	v_pk_mul_f32 v[40:41], v[8:9], v[40:41]
	v_pk_mul_f32 v[38:39], v[6:7], v[38:39]
	v_pk_mul_f32 v[42:43], v[4:5], v[36:37]
	v_pk_mul_f32 v[36:37], v[2:3], v[34:35]
	v_cvt_pk_bf16_f32 v34, v38, v39
	v_cvt_pk_bf16_f32 v35, v40, v41
	v_cvt_pk_bf16_f32 v36, v36, v37
	v_cvt_pk_bf16_f32 v37, v42, v43
	v_pk_mul_f32 v[30:31], v[30:31], v[60:61] op_sel_hi:[1,0]
	v_pk_mul_f32 v[32:33], v[32:33], v[60:61] op_sel_hi:[1,0]
	v_pk_mul_f32 v[26:27], v[26:27], v[60:61] op_sel_hi:[1,0]
	v_pk_mul_f32 v[28:29], v[28:29], v[60:61] op_sel_hi:[1,0]
	global_store_dwordx4 v[56:57], v[34:37], off
	v_pk_mul_f32 v[32:33], v[16:17], v[32:33]
	v_pk_mul_f32 v[30:31], v[14:15], v[30:31]
	v_pk_mul_f32 v[34:35], v[12:13], v[28:29]
	v_pk_mul_f32 v[28:29], v[10:11], v[26:27]
	v_cvt_pk_bf16_f32 v26, v30, v31
	v_cvt_pk_bf16_f32 v27, v32, v33
	v_cvt_pk_bf16_f32 v28, v28, v29
	v_cvt_pk_bf16_f32 v29, v34, v35
	global_store_dwordx4 v[54:55], v[26:29], off offset:1024
	v_pk_mul_f32 v[22:23], v[22:23], v[58:59] op_sel_hi:[1,0]
	v_pk_mul_f32 v[24:25], v[24:25], v[58:59] op_sel_hi:[1,0]
	v_pk_mul_f32 v[18:19], v[18:19], v[58:59] op_sel_hi:[1,0]
	v_pk_mul_f32 v[20:21], v[20:21], v[58:59] op_sel_hi:[1,0]
	v_pk_mul_f32 v[24:25], v[16:17], v[24:25]
	v_pk_mul_f32 v[22:23], v[14:15], v[22:23]
	v_pk_mul_f32 v[26:27], v[12:13], v[20:21]
	v_pk_mul_f32 v[20:21], v[10:11], v[18:19]
	v_cvt_pk_bf16_f32 v18, v22, v23
	v_cvt_pk_bf16_f32 v19, v24, v25
	v_cvt_pk_bf16_f32 v20, v20, v21
	v_cvt_pk_bf16_f32 v21, v26, v27
	global_store_dwordx4 v[56:57], v[18:21], off offset:1024
	s_branch .Ln2_done
; __device__ __forceinline__ void store8bf(bf16_t* p, f32x4 v0, f32x4 v1) { u32x4 w; w.x = cvt_pk_bf16(v0[0], v0[1]); w.y = cvt_pk_bf16(v0[2], v0[3]); w.z = cvt_pk_bf16(v1[0], v1[1]); w.w = cvt_pk_bf16(v1[2], v1[3]); *(u32x4*)p = w; }
; __device__ __forceinline__ void norm_phase(const float* H, const float* g, bf16_t* HN) {
;     ...
;     const float* p = H + (size_t)row * DM + lane * 8; const float* p2 = H + (size_t)row2 * DM + lane * 8; f32x4 v[4], u[4]; float ss = 0.f, ss2 = 0.f;
; #pragma unroll
;     for (int i = 0; i < 4; ++i) { v[i] = *(const f32x4*)(p + 512 * (i >> 1) + 4 * (i & 1)); u[i] = *(const f32x4*)(p2 + 512 * (i >> 1) + 4 * (i & 1)); }
; #pragma unroll
;     for (int i = 0; i < 4; ++i) { ss += v[i][0] * v[i][0] + v[i][1] * v[i][1] + v[i][2] * v[i][2] + v[i][3] * v[i][3]; ss2 += u[i][0] * u[i][0] + u[i][1] * u[i][1] + u[i][2] * u[i][2] + u[i][3] * u[i][3]; }
;     ss = wave_sum(ss); ss2 = wave_sum(ss2); const float rs = rsqrtf(ss * (1.0f / 1024.0f) + 1e-6f), rs2 = rsqrtf(ss2 * (1.0f / 1024.0f) + 1e-6f);
;     bf16_t* q = HN + (size_t)row * DM + lane * 8; bf16_t* q2 = HN + (size_t)row2 * DM + lane * 8;
; #pragma unroll
;     for (int i = 0; i < 2; ++i) { store8bf(q + 512 * i, v[2 * i] * rs * gv[2 * i], v[2 * i + 1] * rs * gv[2 * i + 1]); store8bf(q2 + 512 * i, u[2 * i] * rs2 * gv[2 * i], u[2 * i + 1] * rs2 * gv[2 * i + 1]); }
.Ln2_lastB:
	s_waitcnt vmcnt(0)
	v_mov_b32_e32 v60, v101
	v_mov_b32_e32 v61, v97
	v_mov_b32_e32 v58, v100
	v_mov_b32_e32 v59, v96
	v_pk_mul_f32 v[60:61], v[60:61], v[60:61]
	v_mov_b32_e32 v62, v93
	v_pk_fma_f32 v[58:59], v[58:59], v[58:59], v[60:61]
	v_mov_b32_e32 v60, v102
	v_mov_b32_e32 v61, v98
	v_pk_fma_f32 v[58:59], v[60:61], v[60:61], v[58:59]
	v_mov_b32_e32 v60, v103
	v_mov_b32_e32 v61, v99
	v_mov_b32_e32 v63, v89
	v_pk_fma_f32 v[58:59], v[60:61], v[60:61], v[58:59]
	v_mov_b32_e32 v60, v92
	v_mov_b32_e32 v61, v88
	v_pk_mul_f32 v[62:63], v[62:63], v[62:63]
	v_mov_b32_e32 v64, v83
	v_pk_fma_f32 v[60:61], v[60:61], v[60:61], v[62:63]
	v_mov_b32_e32 v62, v94
	v_mov_b32_e32 v63, v90
	v_pk_fma_f32 v[60:61], v[62:63], v[62:63], v[60:61]
	v_mov_b32_e32 v62, v95
	v_mov_b32_e32 v63, v91
	v_mov_b32_e32 v65, v79
	v_pk_fma_f32 v[60:61], v[62:63], v[62:63], v[60:61]
	v_mov_b32_e32 v62, v82
	v_mov_b32_e32 v63, v78
	v_pk_mul_f32 v[64:65], v[64:65], v[64:65]
	v_mov_b32_e32 v66, v75
	v_pk_fma_f32 v[62:63], v[62:63], v[62:63], v[64:65]
	v_mov_b32_e32 v64, v84
	v_mov_b32_e32 v65, v80
	v_pk_fma_f32 v[62:63], v[64:65], v[64:65], v[62:63]
	v_mov_b32_e32 v64, v85
	v_mov_b32_e32 v65, v81
	v_mov_b32_e32 v67, v71
	v_pk_fma_f32 v[62:63], v[64:65], v[64:65], v[62:63]
	v_mov_b32_e32 v64, v74
	v_mov_b32_e32 v65, v70
	v_pk_mul_f32 v[66:67], v[66:67], v[66:67]
	s_nop 0
	v_pk_fma_f32 v[64:65], v[64:65], v[64:65], v[66:67]
	v_mov_b32_e32 v66, v76
	v_mov_b32_e32 v67, v72
	v_pk_fma_f32 v[64:65], v[66:67], v[66:67], v[64:65]
	v_mov_b32_e32 v66, v77
	v_mov_b32_e32 v67, v73
	v_pk_fma_f32 v[64:65], v[66:67], v[66:67], v[64:65]
	v_mov_b32_e32 v66, v210
	v_mov_b32_e32 v67, v58
	v_lshlrev_b32_e32 v66, 2, v66
	v_xor_b32_e32 v68, 0x80, v66
	v_mov_b32_e32 v66, v210
	v_mov_b32_e32 v58, v61
	v_lshlrev_b32_e32 v66, 2, v66
	v_xor_b32_e32 v69, 0x80, v66
	v_mov_b32_e32 v66, v60
	v_pk_add_f32 v[58:59], v[66:67], v[58:59]
	v_mov_b32_e32 v60, v64
	v_mov_b32_e32 v61, v62
	v_pk_add_f32 v[58:59], v[58:59], v[60:61]
	v_mov_b32_e32 v62, v65
	v_pk_add_f32 v[58:59], v[58:59], v[62:63]
	ds_swizzle_b32 v61, v59 offset:swizzle(SWAP,16)
	ds_swizzle_b32 v60, v58 offset:swizzle(SWAP,16)
	s_waitcnt lgkmcnt(0)
	v_pk_add_f32 v[58:59], v[58:59], v[60:61]
	ds_swizzle_b32 v61, v59 offset:swizzle(SWAP,8)
	ds_swizzle_b32 v60, v58 offset:swizzle(SWAP,8)
	s_waitcnt lgkmcnt(0)
	v_pk_add_f32 v[58:59], v[58:59], v[60:61]
	ds_swizzle_b32 v61, v59 offset:swizzle(SWAP,4)
	ds_swizzle_b32 v60, v58 offset:swizzle(SWAP,4)
	s_waitcnt lgkmcnt(0)
	v_pk_add_f32 v[58:59], v[58:59], v[60:61]
	ds_swizzle_b32 v61, v59 offset:swizzle(SWAP,2)
	ds_swizzle_b32 v60, v58 offset:swizzle(SWAP,2)
	s_waitcnt lgkmcnt(0)
	v_pk_add_f32 v[58:59], v[58:59], v[60:61]
	ds_swizzle_b32 v61, v59 offset:swizzle(SWAP,1)
	ds_swizzle_b32 v60, v58 offset:swizzle(SWAP,1)
	s_waitcnt lgkmcnt(0)
	v_pk_add_f32 v[58:59], v[58:59], v[60:61]
	ds_bpermute_b32 v61, v68, v59
	ds_bpermute_b32 v60, v69, v58
	s_waitcnt lgkmcnt(0)
	v_pk_add_f32 v[58:59], v[58:59], v[60:61]
	s_nop 0
	v_pk_fma_f32 v[58:59], v[58:59], s[58:59], v[154:155] op_sel_hi:[1,0,0]
	s_nop 0
	v_mul_f32_e32 v60, 0x4b800000, v59
	v_cmp_gt_f32_e64 s[4:5], s46, v59
	v_cmp_gt_f32_e32 vcc, s46, v58
	s_nop 0
	v_cndmask_b32_e64 v59, v59, v60, s[4:5]
	v_rsq_f32_e32 v59, v59
	s_nop 0
	v_mul_f32_e32 v60, 0x45800000, v59
	v_cndmask_b32_e64 v60, v59, v60, s[4:5]
	v_mul_f32_e32 v59, 0x4b800000, v58
	v_cndmask_b32_e32 v58, v58, v59, vcc
	v_rsq_f32_e32 v58, v58
	v_pk_mul_f32 v[100:101], v[100:101], v[60:61] op_sel_hi:[1,0]
	v_pk_mul_f32 v[102:103], v[102:103], v[60:61] op_sel_hi:[1,0]
	v_pk_mul_f32 v[96:97], v[96:97], v[60:61] op_sel_hi:[1,0]
	v_mul_f32_e32 v59, 0x45800000, v58
	v_pk_mul_f32 v[98:99], v[98:99], v[60:61] op_sel_hi:[1,0]
	v_cndmask_b32_e32 v58, v58, v59, vcc
	v_pk_mul_f32 v[102:103], v[8:9], v[102:103]
	v_pk_mul_f32 v[100:101], v[6:7], v[100:101]
	v_pk_mul_f32 v[62:63], v[4:5], v[98:99]
	v_pk_mul_f32 v[98:99], v[2:3], v[96:97]
	v_cvt_pk_bf16_f32 v96, v100, v101
	v_cvt_pk_bf16_f32 v97, v102, v103
	v_cvt_pk_bf16_f32 v98, v98, v99
	v_cvt_pk_bf16_f32 v99, v62, v63
	v_pk_mul_f32 v[92:93], v[92:93], v[58:59] op_sel_hi:[1,0]
	v_pk_mul_f32 v[94:95], v[94:95], v[58:59] op_sel_hi:[1,0]
	v_pk_mul_f32 v[88:89], v[88:89], v[58:59] op_sel_hi:[1,0]
	v_pk_mul_f32 v[90:91], v[90:91], v[58:59] op_sel_hi:[1,0]
	global_store_dwordx4 v[128:129], v[96:99], off
	v_pk_mul_f32 v[94:95], v[8:9], v[94:95]
	v_pk_mul_f32 v[92:93], v[6:7], v[92:93]
	v_pk_mul_f32 v[96:97], v[4:5], v[90:91]
	v_pk_mul_f32 v[90:91], v[2:3], v[88:89]
	v_cvt_pk_bf16_f32 v88, v92, v93
	v_cvt_pk_bf16_f32 v89, v94, v95
	v_cvt_pk_bf16_f32 v90, v90, v91
	v_cvt_pk_bf16_f32 v91, v96, v97
	v_pk_mul_f32 v[82:83], v[82:83], v[60:61] op_sel_hi:[1,0]
	v_pk_mul_f32 v[84:85], v[84:85], v[60:61] op_sel_hi:[1,0]
	v_pk_mul_f32 v[78:79], v[78:79], v[60:61] op_sel_hi:[1,0]
	v_pk_mul_f32 v[80:81], v[80:81], v[60:61] op_sel_hi:[1,0]
	global_store_dwordx4 v[130:131], v[88:91], off
	v_pk_mul_f32 v[84:85], v[16:17], v[84:85]
	v_pk_mul_f32 v[82:83], v[14:15], v[82:83]
	v_pk_mul_f32 v[88:89], v[12:13], v[80:81]
	v_pk_mul_f32 v[80:81], v[10:11], v[78:79]
	v_cvt_pk_bf16_f32 v78, v82, v83
	v_cvt_pk_bf16_f32 v79, v84, v85
	v_cvt_pk_bf16_f32 v80, v80, v81
	v_cvt_pk_bf16_f32 v81, v88, v89
	global_store_dwordx4 v[128:129], v[78:81], off offset:1024
	v_pk_mul_f32 v[74:75], v[74:75], v[58:59] op_sel_hi:[1,0]
	v_pk_mul_f32 v[76:77], v[76:77], v[58:59] op_sel_hi:[1,0]
	v_pk_mul_f32 v[70:71], v[70:71], v[58:59] op_sel_hi:[1,0]
	v_pk_mul_f32 v[72:73], v[72:73], v[58:59] op_sel_hi:[1,0]
	v_pk_mul_f32 v[76:77], v[16:17], v[76:77]
	v_pk_mul_f32 v[74:75], v[14:15], v[74:75]
	v_pk_mul_f32 v[78:79], v[12:13], v[72:73]
	v_pk_mul_f32 v[72:73], v[10:11], v[70:71]
	v_cvt_pk_bf16_f32 v70, v74, v75
	v_cvt_pk_bf16_f32 v71, v76, v77
	v_cvt_pk_bf16_f32 v72, v72, v73
	v_cvt_pk_bf16_f32 v73, v78, v79
	global_store_dwordx4 v[130:131], v[70:73], off offset:1024
	s_branch .Ln2_done
; __device__ __forceinline__ void store8bf(bf16_t* p, f32x4 v0, f32x4 v1) { u32x4 w; w.x = cvt_pk_bf16(v0[0], v0[1]); w.y = cvt_pk_bf16(v0[2], v0[3]); w.z = cvt_pk_bf16(v1[0], v1[1]); w.w = cvt_pk_bf16(v1[2], v1[3]); *(u32x4*)p = w; }
; __device__ __forceinline__ void norm_phase(const float* H, const float* g, bf16_t* HN) {
;     ...
;     const float* p = H + (size_t)row * DM + lane * 8; const float* p2 = H + (size_t)row2 * DM + lane * 8; f32x4 v[4], u[4]; float ss = 0.f, ss2 = 0.f;
; #pragma unroll
;     for (int i = 0; i < 4; ++i) { v[i] = *(const f32x4*)(p + 512 * (i >> 1) + 4 * (i & 1)); u[i] = *(const f32x4*)(p2 + 512 * (i >> 1) + 4 * (i & 1)); }
; #pragma unroll
;     for (int i = 0; i < 4; ++i) { ss += v[i][0] * v[i][0] + v[i][1] * v[i][1] + v[i][2] * v[i][2] + v[i][3] * v[i][3]; ss2 += u[i][0] * u[i][0] + u[i][1] * u[i][1] + u[i][2] * u[i][2] + u[i][3] * u[i][3]; }
;     ss = wave_sum(ss); ss2 = wave_sum(ss2); const float rs = rsqrtf(ss * (1.0f / 1024.0f) + 1e-6f), rs2 = rsqrtf(ss2 * (1.0f / 1024.0f) + 1e-6f);
;     bf16_t* q = HN + (size_t)row * DM + lane * 8; bf16_t* q2 = HN + (size_t)row2 * DM + lane * 8;
; #pragma unroll
;     for (int i = 0; i < 2; ++i) { store8bf(q + 512 * i, v[2 * i] * rs * gv[2 * i], v[2 * i + 1] * rs * gv[2 * i + 1]); store8bf(q2 + 512 * i, u[2 * i] * rs2 * gv[2 * i], u[2 * i + 1] * rs2 * gv[2 * i + 1]); }
.Ln2_lastA:
	s_waitcnt vmcnt(0)
	v_mov_b32_e32 v60, v47
	v_mov_b32_e32 v61, v43
	v_mov_b32_e32 v58, v46
	v_mov_b32_e32 v59, v42
	v_pk_mul_f32 v[60:61], v[60:61], v[60:61]
	v_mov_b32_e32 v62, v39
	v_pk_fma_f32 v[58:59], v[58:59], v[58:59], v[60:61]
	v_mov_b32_e32 v60, v48
	v_mov_b32_e32 v61, v44
	v_pk_fma_f32 v[58:59], v[60:61], v[60:61], v[58:59]
	v_mov_b32_e32 v60, v49
	v_mov_b32_e32 v61, v45
	v_mov_b32_e32 v63, v35
	v_pk_fma_f32 v[58:59], v[60:61], v[60:61], v[58:59]
	v_mov_b32_e32 v60, v38
	v_mov_b32_e32 v61, v34
	v_pk_mul_f32 v[62:63], v[62:63], v[62:63]
	v_mov_b32_e32 v64, v31
	v_pk_fma_f32 v[60:61], v[60:61], v[60:61], v[62:63]
	v_mov_b32_e32 v62, v40
	v_mov_b32_e32 v63, v36
	v_pk_fma_f32 v[60:61], v[62:63], v[62:63], v[60:61]
	v_mov_b32_e32 v62, v41
	v_mov_b32_e32 v63, v37
	v_mov_b32_e32 v65, v27
	v_pk_fma_f32 v[60:61], v[62:63], v[62:63], v[60:61]
	v_mov_b32_e32 v62, v30
	v_mov_b32_e32 v63, v26
	v_pk_mul_f32 v[64:65], v[64:65], v[64:65]
	v_mov_b32_e32 v66, v23
	v_pk_fma_f32 v[62:63], v[62:63], v[62:63], v[64:65]
	v_mov_b32_e32 v64, v32
	v_mov_b32_e32 v65, v28
	v_pk_fma_f32 v[62:63], v[64:65], v[64:65], v[62:63]
	v_mov_b32_e32 v64, v33
	v_mov_b32_e32 v65, v29
	v_mov_b32_e32 v67, v19
	v_pk_fma_f32 v[62:63], v[64:65], v[64:65], v[62:63]
	v_mov_b32_e32 v64, v22
	v_mov_b32_e32 v65, v18
	v_pk_mul_f32 v[66:67], v[66:67], v[66:67]
	s_nop 0
	v_pk_fma_f32 v[64:65], v[64:65], v[64:65], v[66:67]
	v_mov_b32_e32 v66, v24
	v_mov_b32_e32 v67, v20
	v_pk_fma_f32 v[64:65], v[66:67], v[66:67], v[64:65]
	v_mov_b32_e32 v66, v25
	v_mov_b32_e32 v67, v21
	v_pk_fma_f32 v[64:65], v[66:67], v[66:67], v[64:65]
	v_mov_b32_e32 v66, v210
	v_mov_b32_e32 v67, v58
	v_lshlrev_b32_e32 v66, 2, v66
	v_xor_b32_e32 v68, 0x80, v66
	v_mov_b32_e32 v66, v210
	v_mov_b32_e32 v58, v61
	v_lshlrev_b32_e32 v66, 2, v66
	v_xor_b32_e32 v69, 0x80, v66
	v_mov_b32_e32 v66, v60
	v_pk_add_f32 v[58:59], v[66:67], v[58:59]
	v_mov_b32_e32 v60, v64
	v_mov_b32_e32 v61, v62
	v_pk_add_f32 v[58:59], v[58:59], v[60:61]
	v_mov_b32_e32 v62, v65
	v_pk_add_f32 v[58:59], v[58:59], v[62:63]
	ds_swizzle_b32 v61, v59 offset:swizzle(SWAP,16)
	ds_swizzle_b32 v60, v58 offset:swizzle(SWAP,16)
	s_waitcnt lgkmcnt(0)
	v_pk_add_f32 v[58:59], v[58:59], v[60:61]
	ds_swizzle_b32 v61, v59 offset:swizzle(SWAP,8)
	ds_swizzle_b32 v60, v58 offset:swizzle(SWAP,8)
	s_waitcnt lgkmcnt(0)
	v_pk_add_f32 v[58:59], v[58:59], v[60:61]
	ds_swizzle_b32 v61, v59 offset:swizzle(SWAP,4)
	ds_swizzle_b32 v60, v58 offset:swizzle(SWAP,4)
	s_waitcnt lgkmcnt(0)
	v_pk_add_f32 v[58:59], v[58:59], v[60:61]
	ds_swizzle_b32 v61, v59 offset:swizzle(SWAP,2)
	ds_swizzle_b32 v60, v58 offset:swizzle(SWAP,2)
	s_waitcnt lgkmcnt(0)
	v_pk_add_f32 v[58:59], v[58:59], v[60:61]
	ds_swizzle_b32 v61, v59 offset:swizzle(SWAP,1)
	ds_swizzle_b32 v60, v58 offset:swizzle(SWAP,1)
	s_waitcnt lgkmcnt(0)
	v_pk_add_f32 v[58:59], v[58:59], v[60:61]
	ds_bpermute_b32 v61, v68, v59
	ds_bpermute_b32 v60, v69, v58
	s_waitcnt lgkmcnt(0)
	v_pk_add_f32 v[58:59], v[58:59], v[60:61]
	s_nop 0
	v_pk_fma_f32 v[58:59], v[58:59], s[58:59], v[154:155] op_sel_hi:[1,0,0]
	s_nop 0
	v_mul_f32_e32 v60, 0x4b800000, v59
	v_cmp_gt_f32_e64 s[4:5], s46, v59
	v_cmp_gt_f32_e32 vcc, s46, v58
	s_nop 0
	v_cndmask_b32_e64 v59, v59, v60, s[4:5]
	v_rsq_f32_e32 v59, v59
	s_nop 0
	v_mul_f32_e32 v60, 0x45800000, v59
	v_cndmask_b32_e64 v60, v59, v60, s[4:5]
	v_mul_f32_e32 v59, 0x4b800000, v58
	v_cndmask_b32_e32 v58, v58, v59, vcc
	v_rsq_f32_e32 v58, v58
	v_pk_mul_f32 v[46:47], v[46:47], v[60:61] op_sel_hi:[1,0]
	v_pk_mul_f32 v[48:49], v[48:49], v[60:61] op_sel_hi:[1,0]
	v_pk_mul_f32 v[42:43], v[42:43], v[60:61] op_sel_hi:[1,0]
	v_mul_f32_e32 v59, 0x45800000, v58
	v_pk_mul_f32 v[44:45], v[44:45], v[60:61] op_sel_hi:[1,0]
	v_cndmask_b32_e32 v58, v58, v59, vcc
	v_pk_mul_f32 v[48:49], v[8:9], v[48:49]
	v_pk_mul_f32 v[46:47], v[6:7], v[46:47]
	v_pk_mul_f32 v[62:63], v[4:5], v[44:45]
	v_pk_mul_f32 v[44:45], v[2:3], v[42:43]
	v_cvt_pk_bf16_f32 v42, v46, v47
	v_cvt_pk_bf16_f32 v43, v48, v49
	v_cvt_pk_bf16_f32 v44, v44, v45
	v_cvt_pk_bf16_f32 v45, v62, v63
	v_pk_mul_f32 v[38:39], v[38:39], v[58:59] op_sel_hi:[1,0]
	v_pk_mul_f32 v[40:41], v[40:41], v[58:59] op_sel_hi:[1,0]
	v_pk_mul_f32 v[34:35], v[34:35], v[58:59] op_sel_hi:[1,0]
	v_pk_mul_f32 v[36:37], v[36:37], v[58:59] op_sel_hi:[1,0]
	global_store_dwordx4 v[54:55], v[42:45], off
	v_pk_mul_f32 v[40:41], v[8:9], v[40:41]
	v_pk_mul_f32 v[38:39], v[6:7], v[38:39]
	v_pk_mul_f32 v[42:43], v[4:5], v[36:37]
	v_pk_mul_f32 v[36:37], v[2:3], v[34:35]
	v_cvt_pk_bf16_f32 v34, v38, v39
	v_cvt_pk_bf16_f32 v35, v40, v41
	v_cvt_pk_bf16_f32 v36, v36, v37
	v_cvt_pk_bf16_f32 v37, v42, v43
	v_pk_mul_f32 v[30:31], v[30:31], v[60:61] op_sel_hi:[1,0]
	v_pk_mul_f32 v[32:33], v[32:33], v[60:61] op_sel_hi:[1,0]
	v_pk_mul_f32 v[26:27], v[26:27], v[60:61] op_sel_hi:[1,0]
	v_pk_mul_f32 v[28:29], v[28:29], v[60:61] op_sel_hi:[1,0]
	global_store_dwordx4 v[56:57], v[34:37], off
	v_pk_mul_f32 v[32:33], v[16:17], v[32:33]
	v_pk_mul_f32 v[30:31], v[14:15], v[30:31]
	v_pk_mul_f32 v[34:35], v[12:13], v[28:29]
	v_pk_mul_f32 v[28:29], v[10:11], v[26:27]
	v_cvt_pk_bf16_f32 v26, v30, v31
	v_cvt_pk_bf16_f32 v27, v32, v33
	v_cvt_pk_bf16_f32 v28, v28, v29
	v_cvt_pk_bf16_f32 v29, v34, v35
	global_store_dwordx4 v[54:55], v[26:29], off offset:1024
	v_pk_mul_f32 v[22:23], v[22:23], v[58:59] op_sel_hi:[1,0]
	v_pk_mul_f32 v[24:25], v[24:25], v[58:59] op_sel_hi:[1,0]
	v_pk_mul_f32 v[18:19], v[18:19], v[58:59] op_sel_hi:[1,0]
	v_pk_mul_f32 v[20:21], v[20:21], v[58:59] op_sel_hi:[1,0]
	v_pk_mul_f32 v[24:25], v[16:17], v[24:25]
	v_pk_mul_f32 v[22:23], v[14:15], v[22:23]
	v_pk_mul_f32 v[26:27], v[12:13], v[20:21]
	v_pk_mul_f32 v[20:21], v[10:11], v[18:19]
	v_cvt_pk_bf16_f32 v18, v22, v23
	v_cvt_pk_bf16_f32 v19, v24, v25
	v_cvt_pk_bf16_f32 v20, v20, v21
	v_cvt_pk_bf16_f32 v21, v26, v27
	global_store_dwordx4 v[56:57], v[18:21], off offset:1024
; __global__ void __launch_bounds__(512) mega(Params P) {
;     ...
;     norm_phase(H, P.ffn_norm + l * DM, HN);
;     grid.sync();
.Ln2_done:
.LBB0_1502:
	s_or_b64 exec, exec, s[6:7]
	s_barrier
	s_mov_b64 s[4:5], exec
	v_readlane_b32 s0, v253, 57
	v_readlane_b32 s1, v253, 58
	s_and_b64 s[0:1], s[4:5], s[0:1]
	s_mov_b64 exec, s[0:1]
	s_cbranch_execz .LBB0_1512
	buffer_wbl2 sc1
	s_load_dwordx2 s[6:7], s[56:57], -0x8
	s_load_dword s0, s[56:57], 0x0
	v_readlane_b32 s1, v253, 55
	s_waitcnt lgkmcnt(0)
	s_and_b32 s1, s1, 7
	s_add_i32 s8, s0, 7
	s_sub_i32 s8, s8, s1
	s_lshr_b32 s8, s8, 3
	s_min_u32 s9, s0, 8
	s_lshl_b32 s1, s1, 2
	s_addk_i32 s1, 0x88
	v_mov_b32_e32 v2, s1
	global_load_dword v0, v1, s[6:7] sc1
	v_mov_b32_e32 v3, 1
	s_waitcnt vmcnt(0)
	v_and_b32_e32 v0, 0xffff0000, v0
	global_atomic_add v3, v2, v3, s[6:7] sc0
	s_waitcnt vmcnt(0)
	v_and_b32_e32 v3, 0xffff, v3
	s_nop 0
	v_readfirstlane_b32 s1, v3
	s_nop 3
	s_add_i32 s0, s8, -1
	s_cmp_lg_u32 s1, s0
	s_cbranch_scc1 .Lgb_poll_5
	s_sub_i32 s1, 0x10000, s8
	v_mov_b32_e32 v3, s1
	global_atomic_add v3, v2, v3, s[6:7] sc0
	s_waitcnt vmcnt(0)
	v_mov_b32_e32 v3, 1
	global_atomic_add v3, v1, v3, s[6:7] sc0
	s_waitcnt vmcnt(0)
	v_and_b32_e32 v3, 0xffff, v3
	s_nop 0
	v_readfirstlane_b32 s1, v3
	s_nop 3
	s_add_i32 s0, s9, -1
	s_cmp_lg_u32 s1, s0
	s_cbranch_scc1 .Lgb_poll_5
	s_sub_i32 s1, 0x10000, s9
	v_mov_b32_e32 v3, s1
	global_atomic_add v1, v3, s[6:7]
